# grid barrier after the input projection becomes an XCD barrier plus a wait on the neighbouring token groups' completion counters (attention halo only spans +-1 group)
# speedup vs baseline: 1.0195x; 1.0038x over previous
; __device__ __forceinline__ unsigned xb_ld(unsigned* p)              { return __hip_atomic_load(p, __ATOMIC_RELAXED, __HIP_MEMORY_SCOPE_AGENT); }
; __device__ __forceinline__ unsigned xb_add(unsigned* p, unsigned v) { return __hip_atomic_fetch_add(p, v, __ATOMIC_RELAXED, __HIP_MEMORY_SCOPE_AGENT); }
; #define XB_SPIN(cond, bar) do { unsigned _sp = 0; while (cond) { __builtin_amdgcn_s_sleep(1); \
;     if ((++_sp & 255u) == 0u) { if (xb_ld(&(bar)[XB_TMO])) break; if (_sp > XB_SPIN_CAP) { atomicAdd(&(bar)[XB_TMO], 1u); break; } } } } while (0)
; __device__ __forceinline__ void xcd_barrier(const XcdBarrier& b) {
;     asm volatile("s_waitcnt vmcnt(0)" ::: "memory");
;     __syncthreads();
;     if (threadIdx.x == 0) {
;         unsigned* bar = b.bar;
;         __builtin_amdgcn_s_waitcnt(0);
;         unsigned nloc = b.st[0], nx = b.st[1];
;         if (nloc == 0u) { xcd_barrier_complete(bar, b.x, nloc, nx); b.st[0] = nloc; b.st[1] = nx; }
;         const unsigned old = xb_add(&bar[XB_XSUB(b.x)], 1u);
;         const unsigned gen = old / nloc;
;         if (old + 1u == (gen + 1u) * nloc) {
;             __builtin_amdgcn_fence(__ATOMIC_RELEASE, "agent");
;             asm volatile("s_waitcnt vmcnt(0)" ::: "memory");
;             const unsigned og = xb_add(&bar[XB_TOP], 1u);
;             const unsigned tg = og / nx;
;             if (og + 1u == (tg + 1u) * nx) xb_add(&bar[XB_TOPGEN], 1u);
;             else XB_SPIN(xb_ld(&bar[XB_TOPGEN]) == tg, bar);
;             __builtin_amdgcn_fence(__ATOMIC_ACQUIRE, "agent");
;             xb_add(&bar[XB_XGEN(b.x)], 1u);
;             asm volatile("s_waitcnt vmcnt(0)" ::: "memory");
;         } else {
;             XB_SPIN(xb_ld(&bar[XB_XGEN(b.x)]) == gen, bar);
;             __builtin_amdgcn_fence(__ATOMIC_ACQUIRE, "agent");
;             asm volatile("s_waitcnt vmcnt(0)" ::: "memory");
;         }
.LBB0_288:
	v_readlane_b32 s4, v254, 16
	v_readlane_b32 s18, v254, 30
	v_readlane_b32 s19, v254, 31
	s_mov_b64 s[42:43], s[18:19]
	s_waitcnt vmcnt(0)
	s_barrier
	s_getreg_b32 s1, hwreg(HW_REG_XCC_ID, 0, 4)
	s_waitcnt vmcnt(0)
	v_readlane_b32 s5, v254, 17
	v_readlane_b32 s6, v254, 18
	v_readlane_b32 s7, v254, 19
	v_readlane_b32 s8, v254, 20
	v_readlane_b32 s9, v254, 21
	v_readlane_b32 s10, v254, 22
	v_readlane_b32 s11, v254, 23
	v_readlane_b32 s12, v254, 24
	v_readlane_b32 s13, v254, 25
	v_readlane_b32 s14, v254, 26
	v_readlane_b32 s15, v254, 27
	v_readlane_b32 s16, v254, 28
	v_readlane_b32 s17, v254, 29
	s_barrier
	s_mov_b64 s[2:3], exec
	v_readlane_b32 s4, v254, 32
	v_readlane_b32 s5, v254, 33
	s_and_b64 s[4:5], s[2:3], s[4:5]
	s_xor_b64 s[34:35], s[4:5], s[2:3]
	s_mov_b64 exec, s[4:5]
	s_cbranch_execz .LBB0_333
	s_waitcnt vmcnt(0) lgkmcnt(0)
	v_mov_b32_e32 v0, 0x20008
	ds_read_b32 v2, v0
	s_waitcnt lgkmcnt(0)
	v_readfirstlane_b32 s4, v2
	s_nop 3
	s_cmp_eq_u32 s4, 1
	s_cbranch_scc0 .Lxg_P1
	v_readlane_b32 s10, v254, 30
	v_readlane_b32 s11, v254, 31
	s_nop 3
	s_and_b32 s12, s1, 15
	s_lshl_b32 s12, s12, 8
	s_add_u32 s6, s10, 0x3000c0
	s_addc_u32 s7, s11, 0
	s_add_u32 s6, s6, s12
	s_addc_u32 s7, s7, 0
	v_mov_b32_e32 v2, s6
	v_mov_b32_e32 v3, s7
	v_mov_b32_e32 v4, 1
	flat_atomic_add v4, v[2:3], v4 sc0
	s_waitcnt vmcnt(0) lgkmcnt(0)
	v_readfirstlane_b32 s12, v4
	s_nop 3
	s_lshr_b32 s13, s12, 5
	s_add_i32 s13, s13, 1
	s_and_b32 s12, s12, 31
	s_and_b32 s14, s33, 7
	s_lshl_b32 s15, s14, 8
	s_add_u32 s6, s10, 0x3000e0
	s_addc_u32 s7, s11, 0
	s_add_u32 s8, s6, s15
	s_addc_u32 s9, s7, 0
	s_cmp_eq_u32 s12, 31
	s_cbranch_scc0 .Lp1_notlast
	buffer_wbl2 sc1
	s_waitcnt vmcnt(0)
	v_mov_b32_e32 v2, s8
	v_mov_b32_e32 v3, s9
	v_mov_b32_e32 v4, 1
	flat_atomic_add v[2:3], v4
	s_waitcnt vmcnt(0) lgkmcnt(0)
.Lp1_notlast:
	v_readlane_b32 s17, v253, 22
	s_nop 3
	s_cmp_lt_u32 s17, 2
	s_cselect_b32 s12, 6, 0
	s_cselect_b32 s15, 1, 7
	s_and_b32 s16, s14, s12
	s_add_i32 s17, s16, s15
	s_sub_i32 s12, s14, 1
	s_max_i32 s16, s12, s16
	s_add_i32 s12, s14, 1
	s_min_i32 s17, s12, s17
	s_lshl_b32 s16, s16, 8
	s_lshl_b32 s17, s17, 8
	s_add_u32 s12, s6, s16
	s_addc_u32 s15, s7, 0
	v_mov_b32_e32 v2, s12
	v_mov_b32_e32 v3, s15
	v_mov_b32_e32 v4, s8
	v_mov_b32_e32 v5, s9
	s_add_u32 s12, s6, s17
	s_addc_u32 s15, s7, 0
	v_mov_b32_e32 v6, s12
	v_mov_b32_e32 v7, s15
	v_mov_b32_e32 v11, s13
	s_mov_b32 s4, 0
.Lp1_spin:
	flat_load_dword v8, v[2:3] sc1
	flat_load_dword v9, v[4:5] sc1
	flat_load_dword v10, v[6:7] sc1
	s_waitcnt vmcnt(0) lgkmcnt(0)
	v_min3_u32 v8, v8, v9, v10
	v_cmp_lt_u32_e32 vcc, v8, v11
	s_cbranch_vccz .Lp1_done
	s_sleep 1
	s_add_i32 s4, s4, 1
	s_cmp_lt_u32 s4, 0x100000
	s_cbranch_scc1 .Lp1_spin

; __device__ __forceinline__ unsigned xb_ld(unsigned* p)              { return __hip_atomic_load(p, __ATOMIC_RELAXED, __HIP_MEMORY_SCOPE_AGENT); }
; __device__ __forceinline__ void xcd_barrier_complete(unsigned* bar, unsigned x, unsigned& nloc, unsigned& nx) {
;     const unsigned G = gridDim.x * gridDim.y * gridDim.z;
;     unsigned sum, cnt, mine, sp = 0u;
;     for (;;) {
;         sum = 0u; cnt = 0u; mine = 0u;
; #pragma unroll
;         for (unsigned j = 0; j < 16; ++j) { const unsigned c = xb_ld(&bar[XB_XCNT(j)]); sum += c; cnt += (c > 0u) ? 1u : 0u; mine = (j == x) ? c : mine; }
;         if (sum == G) break;
;         __builtin_amdgcn_s_sleep(1);
;         if ((++sp & 255u) == 0u) { if (xb_ld(&bar[XB_TMO])) break; if (sp > XB_SPIN_CAP) { atomicAdd(&bar[XB_TMO], 1u); break; } }
;     }
;     nloc = mine > 0u ? mine : 1u; nx = cnt > 0u ? cnt : 1u;
; }
; __device__ __forceinline__ void xcd_barrier(const XcdBarrier& b) {
;     asm volatile("s_waitcnt vmcnt(0)" ::: "memory");
;     __syncthreads();
;     if (threadIdx.x == 0) {
;         unsigned* bar = b.bar;
;         __builtin_amdgcn_s_waitcnt(0);
;         unsigned nloc = b.st[0], nx = b.st[1];
;         if (nloc == 0u) { xcd_barrier_complete(bar, b.x, nloc, nx); b.st[0] = nloc; b.st[1] = nx; }
.Lxg_P1:
	v_readlane_b32 s2, v253, 18
	s_waitcnt vmcnt(0) expcnt(0) lgkmcnt(0)
	s_and_b32 s1, s1, 15
	v_mov_b32_e32 v0, s2
	ds_read_b32 v2, v0
	v_readlane_b32 s2, v253, 19
	s_waitcnt lgkmcnt(0)
	v_cmp_ne_u32_e32 vcc, 0, v2
	v_mov_b32_e32 v0, s2
	ds_read_b32 v0, v0
	s_cbranch_vccnz .LBB0_303
	s_add_u32 s2, s42, 0x300200
	s_addc_u32 s3, s43, 0
	s_add_u32 s4, s42, 0x300400
	s_addc_u32 s5, s43, 0
	s_add_u32 s6, s42, 0x300500
	s_addc_u32 s7, s43, 0
	s_add_u32 s8, s42, 0x300600
	s_addc_u32 s9, s43, 0
	s_add_u32 s10, s42, 0x300700
	s_addc_u32 s11, s43, 0
	s_add_u32 s12, s42, 0x300800
	s_addc_u32 s13, s43, 0
	s_add_u32 s14, s42, 0x300900
	s_addc_u32 s15, s43, 0
	s_add_u32 s16, s42, 0x300a00
	s_addc_u32 s17, s43, 0
	s_add_u32 s18, s42, 0x300b00
	s_addc_u32 s19, s43, 0
	s_add_u32 s20, s42, 0x300c00
	s_addc_u32 s21, s43, 0
	s_add_u32 s22, s42, 0x300d00
	s_addc_u32 s23, s43, 0
	s_add_u32 s24, s42, 0x300e00
	s_addc_u32 s25, s43, 0
	s_add_u32 s26, s42, 0x300f00
	s_addc_u32 s27, s43, 0
	s_add_u32 s28, s42, 0x301000
	s_addc_u32 s29, s43, 0
	s_add_u32 s30, s42, 0x301100
	s_addc_u32 s31, s43, 0
	s_add_u32 s56, s42, 0x301200
	s_addc_u32 s57, s43, 0
	s_add_u32 s72, s42, 0x301300
	s_addc_u32 s73, s43, 0
	s_mov_b32 s39, 1
	s_mov_b64 s[74:75], 0
	s_branch .LBB0_293
.LBB0_291:
	s_or_b64 exec, exec, s[50:51]
	s_andn2_b64 s[48:49], s[94:95], exec
	s_and_b64 s[50:51], s[82:83], exec
	s_or_b64 s[94:95], s[48:49], s[50:51]
	s_andn2_b64 s[48:49], s[78:79], exec
	s_and_b64 s[50:51], s[80:81], exec
	s_or_b64 s[78:79], s[48:49], s[50:51]
